# nt hint on once-read streams (P stores in F / loads in G, fp32 weight loads in conversion, finish/LN1/LN2 row loads); G and L epilogue loads hoisted; no store-order-dependent waits
# speedup vs baseline: 1.0289x; 1.0003x over previous
; __device__ __forceinline__ float bf2f(unsigned b) { return __uint_as_float(b << 16); }
; __device__ __forceinline__ unsigned cvt_pk_bf16(float lo, float hi) { unsigned r; asm volatile("v_cvt_pk_bf16_f32 %0, %1, %2" : "=v"(r) : "v"(lo), "v"(hi)); return r; }
; __device__ __forceinline__ float sigmoid_fast(float x) { return __builtin_amdgcn_rcpf(1.0f + __expf(-x)); }
;     __device__ __forceinline__ void operator()(EPI_SIG) const {
;         const int row0 = u.pm * 256 + wr * 64 + fr, oc = u.pn * 64 + wc * 16 + 4 * fq;
;         f32x4 bv[4];
; #pragma unroll
;         for (int g = 0; g < 4; ++g) bv[g] = *(const f32x4*)(bg + g * 1024 + oc);
; #pragma unroll
;         for (int ai = 0; ai < 2; ++ai)
; #pragma unroll
;             for (int m = 0; m < 4; ++m) { const int row = row0 + ai * 128 + m * 16; const bf16* prow = P + (((((size_t)u.pm * 16 + u.pn) * 2 + ai) * 4 + m) * 8 + (wr * 4 + wc)) * 1024 + (fq * 16 + fr) * 4;
;                 v2u pw[4];
; #pragma unroll
;                 for (int g = 0; g < 4; ++g) pw[g] = *(const v2u*)(prow + g * 256);
;                 f32x4 t = (f32x4){0.f, 0.f, 0.f, 0.f};
; #pragma unroll
;                 for (int bj = 0; bj < 2; ++bj)
; #pragma unroll
;                     for (int n = 0; n < 2; ++n) { const int g = 2 * bj + n; const f32x4 a = acc[ai][bj][m][n] + bv[g];
;                         t[0] += sigmoid_fast(a[0]) * bf2f(pw[g].x & 0xffffu); t[1] += sigmoid_fast(a[1]) * bf2f(pw[g].x >> 16);
;                         t[2] += sigmoid_fast(a[2]) * bf2f(pw[g].y & 0xffffu); t[3] += sigmoid_fast(a[3]) * bf2f(pw[g].y >> 16); }
;                 v2u w; w.x = cvt_pk_bf16(t[0], t[1]); w.y = cvt_pk_bf16(t[2], t[3]);
;                 *(v2u*)(T + (size_t)row * 1024 + oc) = w; }
.LBB0_1859:
	v_lshl_or_b32 v18, s44, 6, v190
	v_ashrrev_i32_e32 v19, 31, v18
	s_nop 7
	s_nop 7
	s_nop 3
	v_lshl_add_u64 v[2:3], v[18:19], 2, s[8:9]
	global_load_dwordx4 v[14:17], v[2:3], off
	v_add_co_u32_e32 v4, vcc, 0x1000, v2
	s_ashr_i32 s47, s46, 31
	s_nop 0
	v_addc_co_u32_e32 v5, vcc, 0, v3, vcc
	global_load_dwordx4 v[10:13], v[4:5], off
	s_ashr_i32 s45, s44, 31
	v_add_co_u32_e32 v4, vcc, 0x2000, v2
	s_lshl_b64 s[2:3], s[46:47], 21
	s_lshl_b64 s[14:15], s[44:45], 17
	v_addc_co_u32_e32 v5, vcc, 0, v3, vcc
	s_add_u32 s44, s2, s14
	v_add_co_u32_e32 v2, vcc, 0x3000, v2
	s_addc_u32 s45, s3, s15
	s_nop 0
	v_addc_co_u32_e32 v3, vcc, 0, v3, vcc
	v_lshl_add_u64 v[24:25], v[168:169], 0, s[44:45]
	global_load_dwordx4 v[6:9], v[4:5], off
	v_lshl_add_u32 v20, s46, 8, v50
	global_load_dwordx4 v[2:5], v[2:3], off
	s_nop 0
	global_load_dwordx2 v[26:27], v[24:25], off nt
	global_load_dwordx2 v[28:29], v[24:25], off offset:512 nt
	global_load_dwordx2 v[22:23], v[24:25], off offset:1024 nt
	s_nop 0
	global_load_dwordx2 v[24:25], v[24:25], off offset:1536 nt
	s_add_u32 s14, s44, 0x10000
	s_addc_u32 s15, s45, 0
	v_lshl_add_u64 v[206:207], v[170:171], 0, s[44:45]
	global_load_dwordx2 v[200:201], v[206:207], off nt
	global_load_dwordx2 v[202:203], v[206:207], off offset:512 nt
	global_load_dwordx2 v[204:205], v[206:207], off offset:1024 nt
	s_nop 0
	global_load_dwordx2 v[206:207], v[206:207], off offset:1536 nt
	v_lshl_add_u64 v[214:215], v[172:173], 0, s[44:45]
	global_load_dwordx2 v[208:209], v[214:215], off nt
	global_load_dwordx2 v[210:211], v[214:215], off offset:512 nt
	global_load_dwordx2 v[212:213], v[214:215], off offset:1024 nt
	s_nop 0
	global_load_dwordx2 v[214:215], v[214:215], off offset:1536 nt
	v_lshl_add_u64 v[222:223], v[174:175], 0, s[44:45]
	global_load_dwordx2 v[216:217], v[222:223], off nt
	global_load_dwordx2 v[218:219], v[222:223], off offset:512 nt
	global_load_dwordx2 v[220:221], v[222:223], off offset:1024 nt
	s_nop 0
	global_load_dwordx2 v[222:223], v[222:223], off offset:1536 nt
	v_lshl_add_u64 v[248:249], v[168:169], 0, s[14:15]
	global_load_dwordx2 v[242:243], v[248:249], off nt
	global_load_dwordx2 v[244:245], v[248:249], off offset:512 nt
	global_load_dwordx2 v[246:247], v[248:249], off offset:1024 nt
	s_nop 0
	global_load_dwordx2 v[248:249], v[248:249], off offset:1536 nt
	s_mov_b32 s2, 0x40000
	s_mov_b32 s58, 0x3f6c835e
	s_mov_b32 s59, 0xbec3ef15
	s_waitcnt vmcnt(16)
	v_pk_add_f32 v[32:33], v[160:161], v[14:15]
	s_nop 0
	v_mul_f32_e32 v21, 0xbfb8aa3b, v32
	v_exp_f32_e32 v21, v21
	v_pk_add_f32 v[30:31], v[162:163], v[16:17]
	v_pk_add_f32 v[144:145], v[144:145], v[14:15]
	v_pk_add_f32 v[128:129], v[128:129], v[14:15]
	v_add_f32_e32 v21, 1.0, v21
	v_rcp_f32_e32 v32, v21
	v_mul_f32_e32 v21, 0xbfb8aa3b, v33
	v_exp_f32_e32 v21, v21
	v_pk_add_f32 v[156:157], v[156:157], v[10:11]
	v_pk_add_f32 v[158:159], v[158:159], v[12:13]
	v_pk_add_f32 v[140:141], v[140:141], v[10:11]
	v_add_f32_e32 v21, 1.0, v21
	v_rcp_f32_e32 v160, v21
	v_mul_f32_e32 v21, 0xbfb8aa3b, v30
	v_exp_f32_e32 v21, v21
	v_pk_add_f32 v[142:143], v[142:143], v[12:13]
	v_pk_add_f32 v[124:125], v[124:125], v[10:11]
	v_pk_add_f32 v[126:127], v[126:127], v[12:13]
	v_add_f32_e32 v21, 1.0, v21
	v_rcp_f32_e32 v30, v21
	v_mul_f32_e32 v21, 0xbfb8aa3b, v31
	v_exp_f32_e32 v21, v21
	v_mul_f32_e32 v31, 0xbfb8aa3b, v157
	v_exp_f32_e32 v31, v31
	s_waitcnt lgkmcnt(0)
	v_lshlrev_b32_e32 v181, 16, v28
	v_add_f32_e32 v21, 1.0, v21
	v_rcp_f32_e32 v162, v21
	v_mul_f32_e32 v21, 0xbfb8aa3b, v156
	v_exp_f32_e32 v21, v21
	v_add_f32_e32 v31, 1.0, v31
	v_lshlrev_b32_e32 v180, 16, v26
	v_rcp_f32_e32 v161, v31
	v_add_f32_e32 v21, 1.0, v21
	v_rcp_f32_e32 v33, v21
	v_pk_add_f32 v[148:149], v[148:149], v[2:3]
	v_pk_add_f32 v[150:151], v[150:151], v[4:5]
	v_pk_add_f32 v[132:133], v[132:133], v[2:3]
	v_pk_mul_f32 v[32:33], v[32:33], v[180:181]
	v_pk_add_f32 v[134:135], v[134:135], v[4:5]
	v_add_f32_e32 v21, 0, v32
	v_add_f32_e32 v21, v21, v33
	v_and_b32_e32 v33, 0xffff0000, v28
	v_and_b32_e32 v32, 0xffff0000, v26
	v_pk_mul_f32 v[32:33], v[160:161], v[32:33]
	v_and_b32_e32 v28, 0xffff0000, v27
	v_add_f32_e32 v26, 0, v32
	v_add_f32_e32 v156, v26, v33
	v_mul_f32_e32 v26, 0xbfb8aa3b, v158
	v_exp_f32_e32 v26, v26
	v_lshlrev_b32_e32 v33, 16, v29
	v_lshlrev_b32_e32 v32, 16, v27
	v_and_b32_e32 v29, 0xffff0000, v29
	v_add_f32_e32 v26, 1.0, v26
	v_rcp_f32_e32 v31, v26
	v_pk_add_f32 v[116:117], v[116:117], v[2:3]
	v_pk_add_f32 v[118:119], v[118:119], v[4:5]
	v_pk_add_f32 v[112:113], v[112:113], v[14:15]
	v_pk_mul_f32 v[30:31], v[30:31], v[32:33]
	v_pk_add_f32 v[108:109], v[108:109], v[10:11]
	v_add_f32_e32 v26, 0, v30
	v_add_f32_e32 v33, v26, v31
	v_mul_f32_e32 v26, 0xbfb8aa3b, v159
	v_exp_f32_e32 v26, v26
	v_pk_add_f32 v[110:111], v[110:111], v[12:13]
	v_pk_add_f32 v[100:101], v[100:101], v[2:3]
	v_pk_add_f32 v[102:103], v[102:103], v[4:5]
	v_add_f32_e32 v26, 1.0, v26
	v_rcp_f32_e32 v163, v26
	v_pk_add_f32 v[92:93], v[92:93], v[10:11]
	v_pk_add_f32 v[94:95], v[94:95], v[12:13]
	v_pk_add_f32 v[84:85], v[84:85], v[2:3]
	v_pk_mul_f32 v[26:27], v[162:163], v[28:29]
	v_pk_add_f32 v[28:29], v[152:153], v[6:7]
	v_add_f32_e32 v26, 0, v26
	v_add_f32_e32 v157, v26, v27
	v_pk_add_f32 v[26:27], v[154:155], v[8:9]
	v_mul_f32_e32 v29, 0xbfb8aa3b, v29
	v_mul_f32_e32 v27, 0xbfb8aa3b, v27
	v_exp_f32_e32 v27, v27
	v_exp_f32_e32 v29, v29
	v_mul_f32_e32 v28, 0xbfb8aa3b, v28
	v_exp_f32_e32 v28, v28
	v_add_f32_e32 v27, 1.0, v27
	v_rcp_f32_e32 v32, v27
	v_mul_f32_e32 v27, 0xbfb8aa3b, v148
	v_exp_f32_e32 v27, v27
	v_add_f32_e32 v29, 1.0, v29
	v_rcp_f32_e32 v30, v29
	v_add_f32_e32 v28, 1.0, v28
	v_add_f32_e32 v27, 1.0, v27
; __device__ __forceinline__ float bf2f(unsigned b) { return __uint_as_float(b << 16); }
; __device__ __forceinline__ unsigned cvt_pk_bf16(float lo, float hi) { unsigned r; asm volatile("v_cvt_pk_bf16_f32 %0, %1, %2" : "=v"(r) : "v"(lo), "v"(hi)); return r; }
; __device__ __forceinline__ float sigmoid_fast(float x) { return __builtin_amdgcn_rcpf(1.0f + __expf(-x)); }
;     __device__ __forceinline__ void operator()(EPI_SIG) const {
;     ...
;             for (int m = 0; m < 4; ++m) { const int row = row0 + ai * 128 + m * 16; const bf16* prow = P + (((((size_t)u.pm * 16 + u.pn) * 2 + ai) * 4 + m) * 8 + (wr * 4 + wc)) * 1024 + (fq * 16 + fr) * 4;
;                 v2u pw[4];
; #pragma unroll
;                 for (int g = 0; g < 4; ++g) pw[g] = *(const v2u*)(prow + g * 256);
;                 f32x4 t = (f32x4){0.f, 0.f, 0.f, 0.f};
; #pragma unroll
;                 for (int bj = 0; bj < 2; ++bj)
; #pragma unroll
;                     for (int n = 0; n < 2; ++n) { const int g = 2 * bj + n; const f32x4 a = acc[ai][bj][m][n] + bv[g];
;                         t[0] += sigmoid_fast(a[0]) * bf2f(pw[g].x & 0xffffu); t[1] += sigmoid_fast(a[1]) * bf2f(pw[g].x >> 16);
;                         t[2] += sigmoid_fast(a[2]) * bf2f(pw[g].y & 0xffffu); t[3] += sigmoid_fast(a[3]) * bf2f(pw[g].y >> 16); }
;                 v2u w; w.x = cvt_pk_bf16(t[0], t[1]); w.y = cvt_pk_bf16(t[2], t[3]);
;                 *(v2u*)(T + (size_t)row * 1024 + oc) = w; }
	v_rcp_f32_e32 v29, v27
	v_mul_f32_e32 v27, 0xbfb8aa3b, v149
	v_exp_f32_e32 v27, v27
	v_rcp_f32_e32 v28, v28
	v_lshlrev_b32_e32 v153, 16, v24
	v_lshlrev_b32_e32 v152, 16, v22
	v_add_f32_e32 v27, 1.0, v27
	v_rcp_f32_e32 v31, v27
	v_pk_mul_f32 v[28:29], v[28:29], v[152:153]
	v_mul_f32_e32 v26, 0xbfb8aa3b, v26
	v_add_f32_e32 v21, v21, v28
	v_add_f32_e32 v21, v21, v29
	v_and_b32_e32 v29, 0xffff0000, v24
	v_and_b32_e32 v28, 0xffff0000, v22
	v_pk_mul_f32 v[28:29], v[30:31], v[28:29]
	v_exp_f32_e32 v26, v26
	v_add_f32_e32 v22, v156, v28
	v_add_f32_e32 v30, v22, v29
	v_mul_f32_e32 v22, 0xbfb8aa3b, v150
	v_exp_f32_e32 v22, v22
	v_add_f32_e32 v26, 1.0, v26
	v_rcp_f32_e32 v26, v26
	v_lshlrev_b32_e32 v29, 16, v25
	v_add_f32_e32 v22, 1.0, v22
	v_rcp_f32_e32 v27, v22
	v_lshlrev_b32_e32 v28, 16, v23
	v_and_b32_e32 v25, 0xffff0000, v25
	v_and_b32_e32 v24, 0xffff0000, v23
	v_pk_mul_f32 v[26:27], v[26:27], v[28:29]
	v_pk_add_f32 v[76:77], v[76:77], v[10:11]
	v_add_f32_e32 v22, v33, v26
	v_add_f32_e32 v26, v22, v27
	v_mul_f32_e32 v22, 0xbfb8aa3b, v151
	v_exp_f32_e32 v22, v22
	v_pk_add_f32 v[78:79], v[78:79], v[12:13]
	v_pk_add_f32 v[68:69], v[68:69], v[2:3]
	v_pk_add_f32 v[60:61], v[60:61], v[10:11]
	v_add_f32_e32 v22, 1.0, v22
	v_rcp_f32_e32 v33, v22
	v_pk_add_f32 v[62:63], v[62:63], v[12:13]
	v_pk_add_f32 v[52:53], v[52:53], v[2:3]
	v_pk_add_f32 v[10:11], v[42:43], v[10:11]
	v_pk_mul_f32 v[22:23], v[32:33], v[24:25]
	v_cvt_pk_bf16_f32 v24, v21, v30
	v_ashrrev_i32_e32 v21, 31, v20
	v_add_f32_e32 v22, v157, v22
	v_add_f32_e32 v22, v22, v23
	v_cvt_pk_bf16_f32 v25, v26, v22
	v_lshlrev_b64 v[22:23], 11, v[20:21]
	v_lshl_add_u64 v[26:27], s[6:7], 0, v[22:23]
	v_lshlrev_b64 v[22:23], 1, v[18:19]
	v_lshl_add_u64 v[18:19], v[26:27], 0, v[22:23]
	global_store_dwordx2 v[18:19], v[24:25], off
	v_mul_f32_e32 v21, 0xbfb8aa3b, v144
	v_exp_f32_e32 v21, v21
	v_pk_add_f32 v[32:33], v[146:147], v[16:17]
	v_mul_f32_e32 v10, 0xbfb8aa3b, v10
	v_exp_f32_e32 v10, v10
	v_add_f32_e32 v21, 1.0, v21
	v_rcp_f32_e32 v144, v21
	v_mul_f32_e32 v21, 0xbfb8aa3b, v145
	v_exp_f32_e32 v21, v21
	v_add_f32_e32 v10, 1.0, v10
	v_pk_add_f32 v[12:13], v[44:45], v[12:13]
	v_pk_add_f32 v[2:3], v[34:35], v[2:3]
	v_add_f32_e32 v21, 1.0, v21
	v_rcp_f32_e32 v146, v21
	v_mul_f32_e32 v21, 0xbfb8aa3b, v32
	v_exp_f32_e32 v21, v21
	v_mul_f32_e32 v2, 0xbfb8aa3b, v2
	v_exp_f32_e32 v2, v2
	v_add_f32_e32 v21, 1.0, v21
	v_rcp_f32_e32 v32, v21
	v_mul_f32_e32 v21, 0xbfb8aa3b, v33
	v_exp_f32_e32 v21, v21
	v_mul_f32_e32 v33, 0xbfb8aa3b, v141
	v_exp_f32_e32 v33, v33
	v_add_f32_e32 v2, 1.0, v2
	v_add_f32_e32 v21, 1.0, v21
	v_rcp_f32_e32 v148, v21
	v_mul_f32_e32 v21, 0xbfb8aa3b, v140
	v_exp_f32_e32 v21, v21
	v_add_f32_e32 v33, 1.0, v33
	v_rcp_f32_e32 v147, v33
	v_add_f32_e32 v21, 1.0, v21
	v_rcp_f32_e32 v145, v21
	s_waitcnt vmcnt(12)
	v_mov_b64_e32 v[28:29], v[200:201]
	v_mov_b64_e32 v[30:31], v[202:203]
	v_mov_b64_e32 v[24:25], v[204:205]
	v_mov_b64_e32 v[26:27], v[206:207]
	v_lshl_add_u64 v[206:207], v[170:171], 0, s[14:15]
	global_load_dwordx2 v[200:201], v[206:207], off nt
	global_load_dwordx2 v[202:203], v[206:207], off offset:512 nt
	global_load_dwordx2 v[204:205], v[206:207], off offset:1024 nt
	s_nop 0
	global_load_dwordx2 v[206:207], v[206:207], off offset:1536 nt
	v_and_b32_e32 v140, 0xffff0000, v28
	v_and_b32_e32 v141, 0xffff0000, v30
	v_lshlrev_b32_e32 v151, 16, v30
	v_lshlrev_b32_e32 v150, 16, v28
	v_pk_mul_f32 v[140:141], v[146:147], v[140:141]
	v_pk_mul_f32 v[144:145], v[144:145], v[150:151]
	v_add_f32_e32 v28, 0, v140
	v_add_f32_e32 v21, 0, v144
	v_add_f32_e32 v144, v28, v141
	v_mul_f32_e32 v28, 0xbfb8aa3b, v142
	v_exp_f32_e32 v28, v28
	v_lshlrev_b32_e32 v141, 16, v31
	v_lshlrev_b32_e32 v140, 16, v29
	v_and_b32_e32 v31, 0xffff0000, v31
	v_add_f32_e32 v28, 1.0, v28
	v_rcp_f32_e32 v33, v28
	v_and_b32_e32 v30, 0xffff0000, v29
	v_add_f32_e32 v21, v21, v145
	v_pk_mul_f32 v[32:33], v[32:33], v[140:141]
	s_nop 0
	v_add_f32_e32 v28, 0, v32
	v_add_f32_e32 v140, v28, v33
	v_mul_f32_e32 v28, 0xbfb8aa3b, v143
	v_exp_f32_e32 v28, v28
	s_nop 0
	v_add_f32_e32 v28, 1.0, v28
	v_rcp_f32_e32 v149, v28
	s_nop 0
	v_pk_mul_f32 v[28:29], v[148:149], v[30:31]
	s_nop 0
	v_add_f32_e32 v28, 0, v28
	v_add_f32_e32 v141, v28, v29
	v_pk_add_f32 v[28:29], v[138:139], v[8:9]
	v_pk_add_f32 v[30:31], v[136:137], v[6:7]
	v_mul_f32_e32 v29, 0xbfb8aa3b, v29
	v_exp_f32_e32 v29, v29
	v_mul_f32_e32 v31, 0xbfb8aa3b, v31
	v_exp_f32_e32 v31, v31
	v_mul_f32_e32 v30, 0xbfb8aa3b, v30
	v_add_f32_e32 v29, 1.0, v29
	v_rcp_f32_e32 v136, v29
	v_mul_f32_e32 v29, 0xbfb8aa3b, v132
	v_exp_f32_e32 v29, v29
	v_exp_f32_e32 v30, v30
	v_add_f32_e32 v31, 1.0, v31
	v_rcp_f32_e32 v32, v31
	v_add_f32_e32 v29, 1.0, v29
	v_rcp_f32_e32 v31, v29
	v_mul_f32_e32 v29, 0xbfb8aa3b, v133
	v_exp_f32_e32 v29, v29
	v_add_f32_e32 v30, 1.0, v30
	v_rcp_f32_e32 v30, v30
	v_lshlrev_b32_e32 v139, 16, v26
	v_add_f32_e32 v29, 1.0, v29
	v_lshlrev_b32_e32 v138, 16, v24
	v_rcp_f32_e32 v33, v29
	v_pk_mul_f32 v[30:31], v[30:31], v[138:139]
	v_mul_f32_e32 v28, 0xbfb8aa3b, v28
	v_add_f32_e32 v21, v21, v30
	v_add_f32_e32 v21, v21, v31
	v_and_b32_e32 v31, 0xffff0000, v26
	v_and_b32_e32 v30, 0xffff0000, v24
	v_pk_mul_f32 v[30:31], v[32:33], v[30:31]
	v_exp_f32_e32 v28, v28
	v_add_f32_e32 v24, v144, v30
	v_add_f32_e32 v32, v24, v31
	v_mul_f32_e32 v24, 0xbfb8aa3b, v134
	v_exp_f32_e32 v24, v24
	v_add_f32_e32 v28, 1.0, v28
	v_rcp_f32_e32 v28, v28
	v_lshlrev_b32_e32 v31, 16, v27
	v_add_f32_e32 v24, 1.0, v24
	v_rcp_f32_e32 v29, v24
	v_lshlrev_b32_e32 v30, 16, v25
	v_and_b32_e32 v27, 0xffff0000, v27
	v_and_b32_e32 v26, 0xffff0000, v25
	v_pk_mul_f32 v[28:29], v[28:29], v[30:31]
	s_nop 0
	v_add_f32_e32 v24, v140, v28
	v_add_f32_e32 v28, v24, v29
	v_mul_f32_e32 v24, 0xbfb8aa3b, v135
	v_exp_f32_e32 v24, v24
	s_nop 0
	v_add_f32_e32 v24, 1.0, v24
	v_rcp_f32_e32 v137, v24
	s_nop 0
	v_pk_mul_f32 v[24:25], v[136:137], v[26:27]
	s_nop 0
	v_add_f32_e32 v24, v141, v24
	v_add_f32_e32 v25, v24, v25
	v_or_b32_e32 v24, 16, v20
	v_cvt_pk_bf16_f32 v26, v21, v32
	v_cvt_pk_bf16_f32 v27, v28, v25
	v_ashrrev_i32_e32 v25, 31, v24
	v_lshlrev_b64 v[24:25], 11, v[24:25]
	v_lshl_add_u64 v[24:25], s[6:7], 0, v[24:25]
	v_lshl_add_u64 v[24:25], v[24:25], 0, v[22:23]
	global_store_dwordx2 v[24:25], v[26:27], off
	v_mul_f32_e32 v21, 0xbfb8aa3b, v128
	v_exp_f32_e32 v21, v21
	v_pk_add_f32 v[32:33], v[130:131], v[16:17]
	v_add_f32_e32 v21, 1.0, v21
	v_rcp_f32_e32 v128, v21
	v_mul_f32_e32 v21, 0xbfb8aa3b, v129
	v_exp_f32_e32 v21, v21
	s_waitcnt vmcnt(12)
; __device__ __forceinline__ float bf2f(unsigned b) { return __uint_as_float(b << 16); }
; __device__ __forceinline__ unsigned cvt_pk_bf16(float lo, float hi) { unsigned r; asm volatile("v_cvt_pk_bf16_f32 %0, %1, %2" : "=v"(r) : "v"(lo), "v"(hi)); return r; }
; __device__ __forceinline__ float sigmoid_fast(float x) { return __builtin_amdgcn_rcpf(1.0f + __expf(-x)); }
;     __device__ __forceinline__ void operator()(EPI_SIG) const {
;     ...
;             for (int m = 0; m < 4; ++m) { const int row = row0 + ai * 128 + m * 16; const bf16* prow = P + (((((size_t)u.pm * 16 + u.pn) * 2 + ai) * 4 + m) * 8 + (wr * 4 + wc)) * 1024 + (fq * 16 + fr) * 4;
;                 v2u pw[4];
; #pragma unroll
;                 for (int g = 0; g < 4; ++g) pw[g] = *(const v2u*)(prow + g * 256);
;                 f32x4 t = (f32x4){0.f, 0.f, 0.f, 0.f};
; #pragma unroll
;                 for (int bj = 0; bj < 2; ++bj)
; #pragma unroll
;                     for (int n = 0; n < 2; ++n) { const int g = 2 * bj + n; const f32x4 a = acc[ai][bj][m][n] + bv[g];
;                         t[0] += sigmoid_fast(a[0]) * bf2f(pw[g].x & 0xffffu); t[1] += sigmoid_fast(a[1]) * bf2f(pw[g].x >> 16);
;                         t[2] += sigmoid_fast(a[2]) * bf2f(pw[g].y & 0xffffu); t[3] += sigmoid_fast(a[3]) * bf2f(pw[g].y >> 16); }
;                 v2u w; w.x = cvt_pk_bf16(t[0], t[1]); w.y = cvt_pk_bf16(t[2], t[3]);
;                 *(v2u*)(T + (size_t)row * 1024 + oc) = w; }
	v_mov_b64_e32 v[28:29], v[208:209]
	v_mov_b64_e32 v[30:31], v[210:211]
	v_mov_b64_e32 v[24:25], v[212:213]
	v_mov_b64_e32 v[26:27], v[214:215]
	v_lshl_add_u64 v[214:215], v[172:173], 0, s[14:15]
	global_load_dwordx2 v[208:209], v[214:215], off nt
	global_load_dwordx2 v[210:211], v[214:215], off offset:512 nt
	global_load_dwordx2 v[212:213], v[214:215], off offset:1024 nt
	s_nop 0
	global_load_dwordx2 v[214:215], v[214:215], off offset:1536 nt
	v_lshlrev_b32_e32 v134, 16, v28
	v_add_f32_e32 v21, 1.0, v21
	v_rcp_f32_e32 v130, v21
	v_mul_f32_e32 v21, 0xbfb8aa3b, v32
	v_exp_f32_e32 v21, v21
	v_lshlrev_b32_e32 v135, 16, v30
	v_add_f32_e32 v21, 1.0, v21
	v_rcp_f32_e32 v32, v21
	v_mul_f32_e32 v21, 0xbfb8aa3b, v33
	v_exp_f32_e32 v21, v21
	v_mul_f32_e32 v33, 0xbfb8aa3b, v125
	v_exp_f32_e32 v33, v33
	v_and_b32_e32 v125, 0xffff0000, v30
	v_add_f32_e32 v21, 1.0, v21
	v_rcp_f32_e32 v132, v21
	v_mul_f32_e32 v21, 0xbfb8aa3b, v124
	v_exp_f32_e32 v21, v21
	v_add_f32_e32 v33, 1.0, v33
	v_rcp_f32_e32 v131, v33
	v_and_b32_e32 v124, 0xffff0000, v28
	v_add_f32_e32 v21, 1.0, v21
	v_rcp_f32_e32 v129, v21
	v_pk_mul_f32 v[124:125], v[130:131], v[124:125]
	v_and_b32_e32 v30, 0xffff0000, v29
	v_add_f32_e32 v28, 0, v124
	v_pk_mul_f32 v[128:129], v[128:129], v[134:135]
	v_lshlrev_b32_e32 v124, 16, v29
	v_add_f32_e32 v21, 0, v128
	v_add_f32_e32 v128, v28, v125
	v_mul_f32_e32 v28, 0xbfb8aa3b, v126
	v_exp_f32_e32 v28, v28
	v_lshlrev_b32_e32 v125, 16, v31
	v_and_b32_e32 v31, 0xffff0000, v31
	v_add_f32_e32 v21, v21, v129
	v_add_f32_e32 v28, 1.0, v28
	v_rcp_f32_e32 v33, v28
	s_nop 0
	v_pk_mul_f32 v[32:33], v[32:33], v[124:125]
	s_nop 0
	v_add_f32_e32 v28, 0, v32
	v_add_f32_e32 v124, v28, v33
	v_mul_f32_e32 v28, 0xbfb8aa3b, v127
	v_exp_f32_e32 v28, v28
	s_nop 0
	v_add_f32_e32 v28, 1.0, v28
	v_rcp_f32_e32 v133, v28
	s_nop 0
	v_pk_mul_f32 v[28:29], v[132:133], v[30:31]
	s_nop 0
	v_add_f32_e32 v28, 0, v28
	v_add_f32_e32 v125, v28, v29
	v_pk_add_f32 v[28:29], v[122:123], v[8:9]
	v_pk_add_f32 v[30:31], v[120:121], v[6:7]
	v_mul_f32_e32 v29, 0xbfb8aa3b, v29
	v_exp_f32_e32 v29, v29
	v_mul_f32_e32 v31, 0xbfb8aa3b, v31
	v_exp_f32_e32 v31, v31
	v_mul_f32_e32 v30, 0xbfb8aa3b, v30
	v_add_f32_e32 v29, 1.0, v29
	v_rcp_f32_e32 v120, v29
	v_mul_f32_e32 v29, 0xbfb8aa3b, v116
	v_exp_f32_e32 v29, v29
	v_exp_f32_e32 v30, v30
	v_add_f32_e32 v31, 1.0, v31
	v_rcp_f32_e32 v32, v31
	v_add_f32_e32 v29, 1.0, v29
	v_rcp_f32_e32 v31, v29
	v_mul_f32_e32 v29, 0xbfb8aa3b, v117
	v_exp_f32_e32 v29, v29
	v_add_f32_e32 v30, 1.0, v30
	v_rcp_f32_e32 v30, v30
	v_lshlrev_b32_e32 v123, 16, v26
	v_add_f32_e32 v29, 1.0, v29
	v_lshlrev_b32_e32 v122, 16, v24
	v_rcp_f32_e32 v33, v29
	v_pk_mul_f32 v[30:31], v[30:31], v[122:123]
	v_mul_f32_e32 v28, 0xbfb8aa3b, v28
	v_add_f32_e32 v21, v21, v30
	v_add_f32_e32 v21, v21, v31
	v_and_b32_e32 v31, 0xffff0000, v26
	v_and_b32_e32 v30, 0xffff0000, v24
	v_pk_mul_f32 v[30:31], v[32:33], v[30:31]
	v_exp_f32_e32 v28, v28
	v_add_f32_e32 v24, v128, v30
	v_add_f32_e32 v32, v24, v31
	v_mul_f32_e32 v24, 0xbfb8aa3b, v118
	v_exp_f32_e32 v24, v24
	v_add_f32_e32 v28, 1.0, v28
	v_rcp_f32_e32 v28, v28
	v_lshlrev_b32_e32 v31, 16, v27
	v_add_f32_e32 v24, 1.0, v24
	v_rcp_f32_e32 v29, v24
	v_lshlrev_b32_e32 v30, 16, v25
	v_and_b32_e32 v27, 0xffff0000, v27
	v_and_b32_e32 v26, 0xffff0000, v25
	v_pk_mul_f32 v[28:29], v[28:29], v[30:31]
	s_nop 0
	v_add_f32_e32 v24, v124, v28
	v_add_f32_e32 v28, v24, v29
	v_mul_f32_e32 v24, 0xbfb8aa3b, v119
	v_exp_f32_e32 v24, v24
	s_nop 0
	v_add_f32_e32 v24, 1.0, v24
	v_rcp_f32_e32 v121, v24
	s_nop 0
	v_pk_mul_f32 v[24:25], v[120:121], v[26:27]
	s_nop 0
	v_add_f32_e32 v24, v125, v24
	v_add_f32_e32 v25, v24, v25
	v_or_b32_e32 v24, 32, v20
	v_cvt_pk_bf16_f32 v26, v21, v32
	v_cvt_pk_bf16_f32 v27, v28, v25
	v_ashrrev_i32_e32 v25, 31, v24
	v_lshlrev_b64 v[24:25], 11, v[24:25]
	v_lshl_add_u64 v[24:25], s[6:7], 0, v[24:25]
	v_lshl_add_u64 v[24:25], v[24:25], 0, v[22:23]
	global_store_dwordx2 v[24:25], v[26:27], off
	v_mul_f32_e32 v21, 0xbfb8aa3b, v112
	v_exp_f32_e32 v21, v21
	v_pk_add_f32 v[32:33], v[114:115], v[16:17]
	v_or_b32_e32 v20, 48, v20
	s_bitset1_b32 s44, 16
	v_add_f32_e32 v21, 1.0, v21
	v_rcp_f32_e32 v112, v21
	v_mul_f32_e32 v21, 0xbfb8aa3b, v113
	v_exp_f32_e32 v21, v21
	s_waitcnt vmcnt(12)
; __device__ __forceinline__ float bf2f(unsigned b) { return __uint_as_float(b << 16); }
; __device__ __forceinline__ unsigned cvt_pk_bf16(float lo, float hi) { unsigned r; asm volatile("v_cvt_pk_bf16_f32 %0, %1, %2" : "=v"(r) : "v"(lo), "v"(hi)); return r; }
; __device__ __forceinline__ float sigmoid_fast(float x) { return __builtin_amdgcn_rcpf(1.0f + __expf(-x)); }
;     __device__ __forceinline__ void operator()(EPI_SIG) const {
;     ...
;             for (int m = 0; m < 4; ++m) { const int row = row0 + ai * 128 + m * 16; const bf16* prow = P + (((((size_t)u.pm * 16 + u.pn) * 2 + ai) * 4 + m) * 8 + (wr * 4 + wc)) * 1024 + (fq * 16 + fr) * 4;
;                 v2u pw[4];
; #pragma unroll
;                 for (int g = 0; g < 4; ++g) pw[g] = *(const v2u*)(prow + g * 256);
;                 f32x4 t = (f32x4){0.f, 0.f, 0.f, 0.f};
; #pragma unroll
;                 for (int bj = 0; bj < 2; ++bj)
; #pragma unroll
;                     for (int n = 0; n < 2; ++n) { const int g = 2 * bj + n; const f32x4 a = acc[ai][bj][m][n] + bv[g];
;                         t[0] += sigmoid_fast(a[0]) * bf2f(pw[g].x & 0xffffu); t[1] += sigmoid_fast(a[1]) * bf2f(pw[g].x >> 16);
;                         t[2] += sigmoid_fast(a[2]) * bf2f(pw[g].y & 0xffffu); t[3] += sigmoid_fast(a[3]) * bf2f(pw[g].y >> 16); }
;                 v2u w; w.x = cvt_pk_bf16(t[0], t[1]); w.y = cvt_pk_bf16(t[2], t[3]);
;                 *(v2u*)(T + (size_t)row * 1024 + oc) = w; }
	v_mov_b64_e32 v[28:29], v[216:217]
	v_mov_b64_e32 v[30:31], v[218:219]
	v_mov_b64_e32 v[24:25], v[220:221]
	v_mov_b64_e32 v[26:27], v[222:223]
	v_lshl_add_u64 v[222:223], v[174:175], 0, s[14:15]
	global_load_dwordx2 v[216:217], v[222:223], off nt
	global_load_dwordx2 v[218:219], v[222:223], off offset:512 nt
	global_load_dwordx2 v[220:221], v[222:223], off offset:1024 nt
	s_nop 0
	global_load_dwordx2 v[222:223], v[222:223], off offset:1536 nt
	v_lshlrev_b32_e32 v118, 16, v28
	v_add_f32_e32 v21, 1.0, v21
	v_rcp_f32_e32 v114, v21
	v_mul_f32_e32 v21, 0xbfb8aa3b, v32
	v_exp_f32_e32 v21, v21
	v_lshlrev_b32_e32 v119, 16, v30
	v_add_f32_e32 v21, 1.0, v21
	v_rcp_f32_e32 v32, v21
	v_mul_f32_e32 v21, 0xbfb8aa3b, v33
	v_exp_f32_e32 v21, v21
	v_mul_f32_e32 v33, 0xbfb8aa3b, v109
	v_exp_f32_e32 v33, v33
	v_and_b32_e32 v109, 0xffff0000, v30
	v_add_f32_e32 v21, 1.0, v21
	v_rcp_f32_e32 v116, v21
	v_mul_f32_e32 v21, 0xbfb8aa3b, v108
	v_exp_f32_e32 v21, v21
	v_add_f32_e32 v33, 1.0, v33
	v_rcp_f32_e32 v115, v33
	v_and_b32_e32 v108, 0xffff0000, v28
	v_add_f32_e32 v21, 1.0, v21
	v_rcp_f32_e32 v113, v21
	v_pk_mul_f32 v[108:109], v[114:115], v[108:109]
	v_and_b32_e32 v30, 0xffff0000, v29
	v_add_f32_e32 v28, 0, v108
	v_pk_mul_f32 v[112:113], v[112:113], v[118:119]
	v_lshlrev_b32_e32 v108, 16, v29
	v_add_f32_e32 v21, 0, v112
	v_add_f32_e32 v112, v28, v109
	v_mul_f32_e32 v28, 0xbfb8aa3b, v110
	v_exp_f32_e32 v28, v28
	v_lshlrev_b32_e32 v109, 16, v31
	v_and_b32_e32 v31, 0xffff0000, v31
	v_add_f32_e32 v21, v21, v113
	v_add_f32_e32 v28, 1.0, v28
	v_rcp_f32_e32 v33, v28
	s_nop 0
	v_pk_mul_f32 v[32:33], v[32:33], v[108:109]
	s_nop 0
	v_add_f32_e32 v28, 0, v32
	v_add_f32_e32 v108, v28, v33
	v_mul_f32_e32 v28, 0xbfb8aa3b, v111
	v_exp_f32_e32 v28, v28
	s_nop 0
	v_add_f32_e32 v28, 1.0, v28
	v_rcp_f32_e32 v117, v28
	s_nop 0
	v_pk_mul_f32 v[28:29], v[116:117], v[30:31]
	s_nop 0
	v_add_f32_e32 v28, 0, v28
	v_add_f32_e32 v109, v28, v29
	v_pk_add_f32 v[28:29], v[106:107], v[8:9]
	v_pk_add_f32 v[30:31], v[104:105], v[6:7]
	v_mul_f32_e32 v29, 0xbfb8aa3b, v29
	v_exp_f32_e32 v29, v29
	v_mul_f32_e32 v31, 0xbfb8aa3b, v31
	v_exp_f32_e32 v31, v31
	v_mul_f32_e32 v30, 0xbfb8aa3b, v30
	v_add_f32_e32 v29, 1.0, v29
	v_rcp_f32_e32 v104, v29
	v_mul_f32_e32 v29, 0xbfb8aa3b, v100
	v_exp_f32_e32 v29, v29
	v_exp_f32_e32 v30, v30
	v_add_f32_e32 v31, 1.0, v31
	v_rcp_f32_e32 v32, v31
	v_add_f32_e32 v29, 1.0, v29
	v_rcp_f32_e32 v31, v29
	v_mul_f32_e32 v29, 0xbfb8aa3b, v101
	v_exp_f32_e32 v29, v29
	v_add_f32_e32 v30, 1.0, v30
	v_rcp_f32_e32 v30, v30
	v_lshlrev_b32_e32 v107, 16, v26
	v_add_f32_e32 v29, 1.0, v29
	v_lshlrev_b32_e32 v106, 16, v24
	v_rcp_f32_e32 v33, v29
	v_pk_mul_f32 v[30:31], v[30:31], v[106:107]
	v_mul_f32_e32 v28, 0xbfb8aa3b, v28
	v_add_f32_e32 v21, v21, v30
	v_add_f32_e32 v21, v21, v31
	v_and_b32_e32 v31, 0xffff0000, v26
	v_and_b32_e32 v30, 0xffff0000, v24
	v_pk_mul_f32 v[30:31], v[32:33], v[30:31]
	v_exp_f32_e32 v28, v28
	v_add_f32_e32 v24, v112, v30
	v_add_f32_e32 v32, v24, v31
	v_mul_f32_e32 v24, 0xbfb8aa3b, v102
	v_exp_f32_e32 v24, v24
	v_add_f32_e32 v28, 1.0, v28
	v_rcp_f32_e32 v28, v28
	v_lshlrev_b32_e32 v31, 16, v27
	v_add_f32_e32 v24, 1.0, v24
	v_rcp_f32_e32 v29, v24
	v_lshlrev_b32_e32 v30, 16, v25
	v_and_b32_e32 v27, 0xffff0000, v27
	v_and_b32_e32 v26, 0xffff0000, v25
	v_pk_mul_f32 v[28:29], v[28:29], v[30:31]
	v_pk_add_f32 v[30:31], v[96:97], v[14:15]
	v_add_f32_e32 v24, v108, v28
	v_add_f32_e32 v28, v24, v29
	v_mul_f32_e32 v24, 0xbfb8aa3b, v103
	v_exp_f32_e32 v24, v24
	v_mul_f32_e32 v30, 0xbfb8aa3b, v30
	v_mul_f32_e32 v31, 0xbfb8aa3b, v31
	v_exp_f32_e32 v30, v30
	v_add_f32_e32 v24, 1.0, v24
	v_rcp_f32_e32 v105, v24
	v_exp_f32_e32 v31, v31
	v_add_f32_e32 v30, 1.0, v30
	v_rcp_f32_e32 v30, v30
	v_pk_mul_f32 v[24:25], v[104:105], v[26:27]
	v_add_f32_e32 v31, 1.0, v31
	v_add_f32_e32 v24, v109, v24
	v_add_f32_e32 v25, v24, v25
	v_cvt_pk_bf16_f32 v24, v21, v32
	v_ashrrev_i32_e32 v21, 31, v20
	v_lshlrev_b64 v[20:21], 11, v[20:21]
	v_lshl_add_u64 v[20:21], s[6:7], 0, v[20:21]
	v_lshl_add_u64 v[20:21], v[20:21], 0, v[22:23]
	v_cvt_pk_bf16_f32 v25, v28, v25
	global_store_dwordx2 v[20:21], v[24:25], off
	v_pk_add_f32 v[28:29], v[98:99], v[16:17]
	v_rcp_f32_e32 v32, v31
	v_mul_f32_e32 v29, 0xbfb8aa3b, v29
	v_exp_f32_e32 v29, v29
	v_mul_f32_e32 v28, 0xbfb8aa3b, v28
	v_exp_f32_e32 v28, v28
	v_add_f32_e32 v29, 1.0, v29
	v_rcp_f32_e32 v96, v29
	v_mul_f32_e32 v29, 0xbfb8aa3b, v92
	v_exp_f32_e32 v29, v29
	v_add_f32_e32 v28, 1.0, v28
	v_rcp_f32_e32 v28, v28
	v_add_f32_e32 v29, 1.0, v29
	v_rcp_f32_e32 v31, v29
	s_waitcnt vmcnt(12)
; __device__ __forceinline__ float bf2f(unsigned b) { return __uint_as_float(b << 16); }
; __device__ __forceinline__ unsigned cvt_pk_bf16(float lo, float hi) { unsigned r; asm volatile("v_cvt_pk_bf16_f32 %0, %1, %2" : "=v"(r) : "v"(lo), "v"(hi)); return r; }
; __device__ __forceinline__ float sigmoid_fast(float x) { return __builtin_amdgcn_rcpf(1.0f + __expf(-x)); }
;     __device__ __forceinline__ void operator()(EPI_SIG) const {
;     ...
;             for (int m = 0; m < 4; ++m) { const int row = row0 + ai * 128 + m * 16; const bf16* prow = P + (((((size_t)u.pm * 16 + u.pn) * 2 + ai) * 4 + m) * 8 + (wr * 4 + wc)) * 1024 + (fq * 16 + fr) * 4;
;                 v2u pw[4];
; #pragma unroll
;                 for (int g = 0; g < 4; ++g) pw[g] = *(const v2u*)(prow + g * 256);
;                 f32x4 t = (f32x4){0.f, 0.f, 0.f, 0.f};
; #pragma unroll
;                 for (int bj = 0; bj < 2; ++bj)
; #pragma unroll
;                     for (int n = 0; n < 2; ++n) { const int g = 2 * bj + n; const f32x4 a = acc[ai][bj][m][n] + bv[g];
;                         t[0] += sigmoid_fast(a[0]) * bf2f(pw[g].x & 0xffffu); t[1] += sigmoid_fast(a[1]) * bf2f(pw[g].x >> 16);
;                         t[2] += sigmoid_fast(a[2]) * bf2f(pw[g].y & 0xffffu); t[3] += sigmoid_fast(a[3]) * bf2f(pw[g].y >> 16); }
;                 v2u w; w.x = cvt_pk_bf16(t[0], t[1]); w.y = cvt_pk_bf16(t[2], t[3]);
;                 *(v2u*)(T + (size_t)row * 1024 + oc) = w; }
	v_mov_b64_e32 v[24:25], v[242:243]
	v_mov_b64_e32 v[26:27], v[244:245]
	v_mov_b64_e32 v[20:21], v[246:247]
	v_mov_b64_e32 v[22:23], v[248:249]
	v_lshlrev_b32_e32 v98, 16, v24
	v_lshlrev_b32_e32 v99, 16, v26
	v_pk_mul_f32 v[30:31], v[30:31], v[98:99]
	s_nop 0
	v_add_f32_e32 v29, 0, v30
	v_add_f32_e32 v92, v29, v31
	v_mul_f32_e32 v29, 0xbfb8aa3b, v93
	v_exp_f32_e32 v29, v29
	v_and_b32_e32 v31, 0xffff0000, v26
	v_and_b32_e32 v30, 0xffff0000, v24
	v_and_b32_e32 v26, 0xffff0000, v25
	v_add_f32_e32 v29, 1.0, v29
	v_rcp_f32_e32 v33, v29
	s_nop 0
	v_pk_mul_f32 v[30:31], v[32:33], v[30:31]
	s_nop 0
	v_add_f32_e32 v24, 0, v30
	v_add_f32_e32 v93, v24, v31
	v_mul_f32_e32 v24, 0xbfb8aa3b, v94
	v_exp_f32_e32 v24, v24
	v_lshlrev_b32_e32 v31, 16, v27
	v_lshlrev_b32_e32 v30, 16, v25
	v_and_b32_e32 v27, 0xffff0000, v27
	v_add_f32_e32 v24, 1.0, v24
	v_rcp_f32_e32 v29, v24
	v_pk_add_f32 v[32:33], v[86:87], v[4:5]
	v_lshlrev_b32_e32 v87, 16, v22
	v_lshlrev_b32_e32 v86, 16, v20
	v_pk_mul_f32 v[28:29], v[28:29], v[30:31]
	s_nop 0
	v_add_f32_e32 v24, 0, v28
	v_add_f32_e32 v31, v24, v29
	v_mul_f32_e32 v24, 0xbfb8aa3b, v95
	v_exp_f32_e32 v24, v24
	s_nop 0
	v_add_f32_e32 v24, 1.0, v24
	v_rcp_f32_e32 v97, v24
	s_nop 0
	v_pk_mul_f32 v[24:25], v[96:97], v[26:27]
	s_nop 0
	v_add_f32_e32 v24, 0, v24
	v_add_f32_e32 v94, v24, v25
	v_pk_add_f32 v[24:25], v[90:91], v[8:9]
	v_pk_add_f32 v[26:27], v[88:89], v[6:7]
	v_mul_f32_e32 v25, 0xbfb8aa3b, v25
	v_exp_f32_e32 v25, v25
	v_mul_f32_e32 v26, 0xbfb8aa3b, v26
	v_mul_f32_e32 v27, 0xbfb8aa3b, v27
	v_exp_f32_e32 v26, v26
	v_add_f32_e32 v25, 1.0, v25
	v_rcp_f32_e32 v30, v25
	v_mul_f32_e32 v25, 0xbfb8aa3b, v84
	v_exp_f32_e32 v27, v27
	v_exp_f32_e32 v25, v25
	v_add_f32_e32 v26, 1.0, v26
	v_rcp_f32_e32 v26, v26
	v_add_f32_e32 v27, 1.0, v27
	v_add_f32_e32 v25, 1.0, v25
	v_rcp_f32_e32 v28, v27
	v_rcp_f32_e32 v27, v25
	v_mul_f32_e32 v24, 0xbfb8aa3b, v24
	v_exp_f32_e32 v24, v24
	v_pk_mul_f32 v[26:27], v[26:27], v[86:87]
	s_nop 0
	v_add_f32_e32 v25, v92, v26
	v_add_f32_e32 v84, v25, v27
	v_mul_f32_e32 v25, 0xbfb8aa3b, v85
	v_exp_f32_e32 v25, v25
	v_and_b32_e32 v27, 0xffff0000, v22
	v_and_b32_e32 v26, 0xffff0000, v20
	v_add_f32_e32 v24, 1.0, v24
	v_add_f32_e32 v25, 1.0, v25
	v_rcp_f32_e32 v29, v25
	v_rcp_f32_e32 v24, v24
	v_and_b32_e32 v22, 0xffff0000, v21
	v_pk_mul_f32 v[26:27], v[28:29], v[26:27]
	s_nop 0
	v_add_f32_e32 v20, v93, v26
	v_add_f32_e32 v28, v20, v27
	v_mul_f32_e32 v20, 0xbfb8aa3b, v32
	v_exp_f32_e32 v20, v20
	v_lshlrev_b32_e32 v27, 16, v23
	v_lshlrev_b32_e32 v26, 16, v21
	v_and_b32_e32 v23, 0xffff0000, v23
	v_add_f32_e32 v20, 1.0, v20
	v_rcp_f32_e32 v25, v20
	s_nop 0
	v_pk_mul_f32 v[24:25], v[24:25], v[26:27]
	s_nop 0
	v_add_f32_e32 v20, v31, v24
	v_add_f32_e32 v24, v20, v25
	v_mul_f32_e32 v20, 0xbfb8aa3b, v33
	v_exp_f32_e32 v20, v20
	s_nop 0
	v_add_f32_e32 v20, 1.0, v20
	v_rcp_f32_e32 v31, v20
	s_nop 0
	v_pk_mul_f32 v[20:21], v[30:31], v[22:23]
	s_nop 0
	v_add_f32_e32 v20, v94, v20
	v_add_co_u32_e32 v22, vcc, s2, v18
	v_add_f32_e32 v21, v20, v21
	s_nop 0
	v_addc_co_u32_e32 v23, vcc, 0, v19, vcc
	v_cvt_pk_bf16_f32 v20, v84, v28
	v_cvt_pk_bf16_f32 v21, v24, v21
	global_store_dwordx2 v[22:23], v[20:21], off
	v_pk_add_f32 v[28:29], v[82:83], v[16:17]
	v_pk_add_f32 v[30:31], v[80:81], v[14:15]
	v_mul_f32_e32 v29, 0xbfb8aa3b, v29
	v_exp_f32_e32 v29, v29
	v_mul_f32_e32 v30, 0xbfb8aa3b, v30
	v_mul_f32_e32 v31, 0xbfb8aa3b, v31
	v_exp_f32_e32 v30, v30
	v_add_f32_e32 v29, 1.0, v29
	v_rcp_f32_e32 v80, v29
	v_mul_f32_e32 v29, 0xbfb8aa3b, v76
	v_exp_f32_e32 v31, v31
	v_exp_f32_e32 v29, v29
	v_add_f32_e32 v30, 1.0, v30
	v_rcp_f32_e32 v30, v30
	v_add_f32_e32 v31, 1.0, v31
	v_add_f32_e32 v29, 1.0, v29
	v_rcp_f32_e32 v32, v31
	v_rcp_f32_e32 v31, v29
	v_mul_f32_e32 v28, 0xbfb8aa3b, v28
	v_exp_f32_e32 v28, v28
	s_mov_b32 s2, 0x48000
	v_add_f32_e32 v28, 1.0, v28
	v_rcp_f32_e32 v28, v28
	s_waitcnt vmcnt(8)
	v_mov_b64_e32 v[24:25], v[200:201]
	v_mov_b64_e32 v[26:27], v[202:203]
	v_mov_b64_e32 v[20:21], v[204:205]
	v_mov_b64_e32 v[22:23], v[206:207]
	v_lshlrev_b32_e32 v82, 16, v24
	v_lshlrev_b32_e32 v83, 16, v26
	v_pk_mul_f32 v[30:31], v[30:31], v[82:83]
	s_nop 0
	v_add_f32_e32 v29, 0, v30
	v_add_f32_e32 v76, v29, v31
	v_mul_f32_e32 v29, 0xbfb8aa3b, v77
	v_exp_f32_e32 v29, v29
	v_and_b32_e32 v31, 0xffff0000, v26
	v_and_b32_e32 v30, 0xffff0000, v24
	v_and_b32_e32 v26, 0xffff0000, v25
	v_add_f32_e32 v29, 1.0, v29
	v_rcp_f32_e32 v33, v29
	s_nop 0
	v_pk_mul_f32 v[30:31], v[32:33], v[30:31]
	s_nop 0
	v_add_f32_e32 v24, 0, v30
	v_add_f32_e32 v77, v24, v31
	v_mul_f32_e32 v24, 0xbfb8aa3b, v78
	v_exp_f32_e32 v24, v24
	v_lshlrev_b32_e32 v31, 16, v27
	v_lshlrev_b32_e32 v30, 16, v25
	v_and_b32_e32 v27, 0xffff0000, v27
	v_add_f32_e32 v24, 1.0, v24
	v_rcp_f32_e32 v29, v24
	v_pk_add_f32 v[32:33], v[70:71], v[4:5]
	v_lshlrev_b32_e32 v71, 16, v22
	v_lshlrev_b32_e32 v70, 16, v20
	v_pk_mul_f32 v[28:29], v[28:29], v[30:31]
	s_nop 0
	v_add_f32_e32 v24, 0, v28
	v_add_f32_e32 v31, v24, v29
	v_mul_f32_e32 v24, 0xbfb8aa3b, v79
	v_exp_f32_e32 v24, v24
	s_nop 0
	v_add_f32_e32 v24, 1.0, v24
	v_rcp_f32_e32 v81, v24
	s_nop 0
	v_pk_mul_f32 v[24:25], v[80:81], v[26:27]
	s_nop 0
	v_add_f32_e32 v24, 0, v24
	v_add_f32_e32 v78, v24, v25
	v_pk_add_f32 v[24:25], v[74:75], v[8:9]
	v_pk_add_f32 v[26:27], v[72:73], v[6:7]
	v_mul_f32_e32 v25, 0xbfb8aa3b, v25
	v_exp_f32_e32 v25, v25
	v_mul_f32_e32 v26, 0xbfb8aa3b, v26
	v_mul_f32_e32 v27, 0xbfb8aa3b, v27
	v_exp_f32_e32 v26, v26
	v_add_f32_e32 v25, 1.0, v25
	v_rcp_f32_e32 v30, v25
	v_mul_f32_e32 v25, 0xbfb8aa3b, v68
	v_exp_f32_e32 v27, v27
	v_exp_f32_e32 v25, v25
	v_add_f32_e32 v26, 1.0, v26
	v_rcp_f32_e32 v26, v26
	v_add_f32_e32 v27, 1.0, v27
; __device__ __forceinline__ float bf2f(unsigned b) { return __uint_as_float(b << 16); }
; __device__ __forceinline__ unsigned cvt_pk_bf16(float lo, float hi) { unsigned r; asm volatile("v_cvt_pk_bf16_f32 %0, %1, %2" : "=v"(r) : "v"(lo), "v"(hi)); return r; }
; __device__ __forceinline__ float sigmoid_fast(float x) { return __builtin_amdgcn_rcpf(1.0f + __expf(-x)); }
;     __device__ __forceinline__ void operator()(EPI_SIG) const {
;     ...
;             for (int m = 0; m < 4; ++m) { const int row = row0 + ai * 128 + m * 16; const bf16* prow = P + (((((size_t)u.pm * 16 + u.pn) * 2 + ai) * 4 + m) * 8 + (wr * 4 + wc)) * 1024 + (fq * 16 + fr) * 4;
;                 v2u pw[4];
; #pragma unroll
;                 for (int g = 0; g < 4; ++g) pw[g] = *(const v2u*)(prow + g * 256);
;                 f32x4 t = (f32x4){0.f, 0.f, 0.f, 0.f};
; #pragma unroll
;                 for (int bj = 0; bj < 2; ++bj)
; #pragma unroll
;                     for (int n = 0; n < 2; ++n) { const int g = 2 * bj + n; const f32x4 a = acc[ai][bj][m][n] + bv[g];
;                         t[0] += sigmoid_fast(a[0]) * bf2f(pw[g].x & 0xffffu); t[1] += sigmoid_fast(a[1]) * bf2f(pw[g].x >> 16);
;                         t[2] += sigmoid_fast(a[2]) * bf2f(pw[g].y & 0xffffu); t[3] += sigmoid_fast(a[3]) * bf2f(pw[g].y >> 16); }
;                 v2u w; w.x = cvt_pk_bf16(t[0], t[1]); w.y = cvt_pk_bf16(t[2], t[3]);
;                 *(v2u*)(T + (size_t)row * 1024 + oc) = w; }
	v_add_f32_e32 v25, 1.0, v25
	v_rcp_f32_e32 v28, v27
	v_rcp_f32_e32 v27, v25
	v_mul_f32_e32 v24, 0xbfb8aa3b, v24
	v_exp_f32_e32 v24, v24
	v_pk_mul_f32 v[26:27], v[26:27], v[70:71]
	s_nop 0
	v_add_f32_e32 v25, v76, v26
	v_add_f32_e32 v68, v25, v27
	v_mul_f32_e32 v25, 0xbfb8aa3b, v69
	v_exp_f32_e32 v25, v25
	v_and_b32_e32 v27, 0xffff0000, v22
	v_and_b32_e32 v26, 0xffff0000, v20
	v_add_f32_e32 v24, 1.0, v24
	v_add_f32_e32 v25, 1.0, v25
	v_rcp_f32_e32 v29, v25
	v_rcp_f32_e32 v24, v24
	v_and_b32_e32 v22, 0xffff0000, v21
	v_pk_mul_f32 v[26:27], v[28:29], v[26:27]
	s_nop 0
	v_add_f32_e32 v20, v77, v26
	v_add_f32_e32 v28, v20, v27
	v_mul_f32_e32 v20, 0xbfb8aa3b, v32
	v_exp_f32_e32 v20, v20
	v_lshlrev_b32_e32 v27, 16, v23
	v_lshlrev_b32_e32 v26, 16, v21
	v_and_b32_e32 v23, 0xffff0000, v23
	v_add_f32_e32 v20, 1.0, v20
	v_rcp_f32_e32 v25, v20
	s_nop 0
	v_pk_mul_f32 v[24:25], v[24:25], v[26:27]
	s_nop 0
	v_add_f32_e32 v20, v31, v24
	v_add_f32_e32 v24, v20, v25
	v_mul_f32_e32 v20, 0xbfb8aa3b, v33
	v_exp_f32_e32 v20, v20
	s_nop 0
	v_add_f32_e32 v20, 1.0, v20
	v_rcp_f32_e32 v31, v20
	s_nop 0
	v_pk_mul_f32 v[20:21], v[30:31], v[22:23]
	s_nop 0
	v_add_f32_e32 v20, v78, v20
	v_add_co_u32_e32 v22, vcc, s2, v18
	v_add_f32_e32 v21, v20, v21
	s_nop 0
	v_addc_co_u32_e32 v23, vcc, 0, v19, vcc
	v_cvt_pk_bf16_f32 v20, v68, v28
	v_cvt_pk_bf16_f32 v21, v24, v21
	global_store_dwordx2 v[22:23], v[20:21], off
	v_pk_add_f32 v[28:29], v[66:67], v[16:17]
	v_pk_add_f32 v[30:31], v[64:65], v[14:15]
	v_mul_f32_e32 v29, 0xbfb8aa3b, v29
	v_exp_f32_e32 v29, v29
	v_mul_f32_e32 v30, 0xbfb8aa3b, v30
	v_mul_f32_e32 v31, 0xbfb8aa3b, v31
	v_exp_f32_e32 v30, v30
	v_add_f32_e32 v29, 1.0, v29
	v_rcp_f32_e32 v64, v29
	v_mul_f32_e32 v29, 0xbfb8aa3b, v60
	v_exp_f32_e32 v31, v31
	v_exp_f32_e32 v29, v29
	v_add_f32_e32 v30, 1.0, v30
	v_rcp_f32_e32 v30, v30
	v_add_f32_e32 v31, 1.0, v31
	v_add_f32_e32 v29, 1.0, v29
	v_rcp_f32_e32 v32, v31
	v_rcp_f32_e32 v31, v29
	v_mul_f32_e32 v28, 0xbfb8aa3b, v28
	v_exp_f32_e32 v28, v28
	s_mov_b32 s2, 0x50000
	v_pk_add_f32 v[14:15], v[46:47], v[14:15]
	v_pk_add_f32 v[16:17], v[48:49], v[16:17]
	v_add_f32_e32 v28, 1.0, v28
	v_rcp_f32_e32 v28, v28
	v_mul_f32_e32 v15, 0xbfb8aa3b, v15
	v_exp_f32_e32 v15, v15
	v_mul_f32_e32 v14, 0xbfb8aa3b, v14
	v_exp_f32_e32 v14, v14
	v_add_f32_e32 v15, 1.0, v15
	v_add_f32_e32 v14, 1.0, v14
	v_rcp_f32_e32 v14, v14
	s_waitcnt vmcnt(4)
	v_mov_b64_e32 v[24:25], v[208:209]
	v_mov_b64_e32 v[26:27], v[210:211]
	v_mov_b64_e32 v[20:21], v[212:213]
	v_mov_b64_e32 v[22:23], v[214:215]
	v_lshlrev_b32_e32 v66, 16, v24
	v_lshlrev_b32_e32 v67, 16, v26
	v_pk_mul_f32 v[30:31], v[30:31], v[66:67]
	s_nop 0
	v_add_f32_e32 v29, 0, v30
	v_add_f32_e32 v60, v29, v31
	v_mul_f32_e32 v29, 0xbfb8aa3b, v61
	v_exp_f32_e32 v29, v29
	v_and_b32_e32 v31, 0xffff0000, v26
	v_and_b32_e32 v30, 0xffff0000, v24
	v_and_b32_e32 v26, 0xffff0000, v25
	v_add_f32_e32 v29, 1.0, v29
	v_rcp_f32_e32 v33, v29
	s_nop 0
	v_pk_mul_f32 v[30:31], v[32:33], v[30:31]
	s_nop 0
	v_add_f32_e32 v24, 0, v30
	v_add_f32_e32 v61, v24, v31
	v_mul_f32_e32 v24, 0xbfb8aa3b, v62
	v_exp_f32_e32 v24, v24
	v_lshlrev_b32_e32 v31, 16, v27
	v_lshlrev_b32_e32 v30, 16, v25
	v_and_b32_e32 v27, 0xffff0000, v27
	v_add_f32_e32 v24, 1.0, v24
	v_rcp_f32_e32 v29, v24
	v_pk_add_f32 v[32:33], v[54:55], v[4:5]
	v_lshlrev_b32_e32 v55, 16, v22
	v_lshlrev_b32_e32 v54, 16, v20
	v_pk_mul_f32 v[28:29], v[28:29], v[30:31]
	v_pk_add_f32 v[4:5], v[36:37], v[4:5]
	v_add_f32_e32 v24, 0, v28
	v_add_f32_e32 v31, v24, v29
	v_mul_f32_e32 v24, 0xbfb8aa3b, v63
	v_exp_f32_e32 v24, v24
	s_nop 0
	v_add_f32_e32 v24, 1.0, v24
	v_rcp_f32_e32 v65, v24
	s_nop 0
	v_pk_mul_f32 v[24:25], v[64:65], v[26:27]
	s_nop 0
	v_add_f32_e32 v24, 0, v24
	v_add_f32_e32 v62, v24, v25
	v_pk_add_f32 v[24:25], v[58:59], v[8:9]
	v_pk_add_f32 v[26:27], v[56:57], v[6:7]
	v_mul_f32_e32 v25, 0xbfb8aa3b, v25
	v_exp_f32_e32 v25, v25
	v_mul_f32_e32 v26, 0xbfb8aa3b, v26
	v_mul_f32_e32 v27, 0xbfb8aa3b, v27
	v_exp_f32_e32 v26, v26
	v_add_f32_e32 v25, 1.0, v25
	v_rcp_f32_e32 v30, v25
	v_mul_f32_e32 v25, 0xbfb8aa3b, v52
	v_exp_f32_e32 v27, v27
	v_exp_f32_e32 v25, v25
	v_add_f32_e32 v26, 1.0, v26
	v_rcp_f32_e32 v26, v26
	v_add_f32_e32 v27, 1.0, v27
	v_add_f32_e32 v25, 1.0, v25
	v_rcp_f32_e32 v28, v27
	v_rcp_f32_e32 v27, v25
	v_mul_f32_e32 v24, 0xbfb8aa3b, v24
	v_exp_f32_e32 v24, v24
	v_pk_add_f32 v[6:7], v[38:39], v[6:7]
	v_pk_mul_f32 v[26:27], v[26:27], v[54:55]
	v_mul_f32_e32 v7, 0xbfb8aa3b, v7
	v_add_f32_e32 v25, v60, v26
	v_add_f32_e32 v52, v25, v27
	v_mul_f32_e32 v25, 0xbfb8aa3b, v53
	v_exp_f32_e32 v25, v25
	v_and_b32_e32 v27, 0xffff0000, v22
	v_and_b32_e32 v26, 0xffff0000, v20
	v_add_f32_e32 v24, 1.0, v24
	v_add_f32_e32 v25, 1.0, v25
	v_rcp_f32_e32 v29, v25
	v_rcp_f32_e32 v24, v24
	v_and_b32_e32 v22, 0xffff0000, v21
	v_exp_f32_e32 v7, v7
	v_pk_mul_f32 v[26:27], v[28:29], v[26:27]
	v_pk_add_f32 v[8:9], v[40:41], v[8:9]
	v_add_f32_e32 v20, v61, v26
	v_add_f32_e32 v28, v20, v27
	v_mul_f32_e32 v20, 0xbfb8aa3b, v32
	v_exp_f32_e32 v20, v20
	v_lshlrev_b32_e32 v27, 16, v23
	v_lshlrev_b32_e32 v26, 16, v21
	v_and_b32_e32 v23, 0xffff0000, v23
	v_add_f32_e32 v20, 1.0, v20
	v_rcp_f32_e32 v25, v20
	v_add_f32_e32 v7, 1.0, v7
	v_mul_f32_e32 v6, 0xbfb8aa3b, v6
	v_exp_f32_e32 v6, v6
	v_pk_mul_f32 v[24:25], v[24:25], v[26:27]
	v_add_f32_e32 v6, 1.0, v6
	v_add_f32_e32 v20, v31, v24
	v_add_f32_e32 v24, v20, v25
	v_mul_f32_e32 v20, 0xbfb8aa3b, v33
	v_exp_f32_e32 v20, v20
	v_rcp_f32_e32 v6, v6
	v_add_f32_e32 v20, 1.0, v20
	v_rcp_f32_e32 v31, v20
	s_nop 0
	v_pk_mul_f32 v[20:21], v[30:31], v[22:23]
	s_nop 0
	v_add_f32_e32 v20, v62, v20
	v_add_co_u32_e32 v22, vcc, s2, v18
	v_add_f32_e32 v21, v20, v21
	s_nop 0
	v_addc_co_u32_e32 v23, vcc, 0, v19, vcc
	v_cvt_pk_bf16_f32 v20, v52, v28
	v_cvt_pk_bf16_f32 v21, v24, v21
	global_store_dwordx2 v[22:23], v[20:21], off
	v_rcp_f32_e32 v28, v15
	v_mul_f32_e32 v15, 0xbfb8aa3b, v16
	v_exp_f32_e32 v15, v15
	s_mov_b64 s[2:3], -1
	v_add_f32_e32 v15, 1.0, v15
	v_rcp_f32_e32 v16, v15
	v_mul_f32_e32 v15, 0xbfb8aa3b, v17
	v_exp_f32_e32 v15, v15
	s_waitcnt vmcnt(0)
; __device__ __forceinline__ float bf2f(unsigned b) { return __uint_as_float(b << 16); }
; __device__ __forceinline__ unsigned cvt_pk_bf16(float lo, float hi) { unsigned r; asm volatile("v_cvt_pk_bf16_f32 %0, %1, %2" : "=v"(r) : "v"(lo), "v"(hi)); return r; }
; __device__ __forceinline__ float sigmoid_fast(float x) { return __builtin_amdgcn_rcpf(1.0f + __expf(-x)); }
;     __device__ __forceinline__ void operator()(EPI_SIG) const {
;     ...
;             for (int m = 0; m < 4; ++m) { const int row = row0 + ai * 128 + m * 16; const bf16* prow = P + (((((size_t)u.pm * 16 + u.pn) * 2 + ai) * 4 + m) * 8 + (wr * 4 + wc)) * 1024 + (fq * 16 + fr) * 4;
;                 v2u pw[4];
; #pragma unroll
;                 for (int g = 0; g < 4; ++g) pw[g] = *(const v2u*)(prow + g * 256);
;                 f32x4 t = (f32x4){0.f, 0.f, 0.f, 0.f};
; #pragma unroll
;                 for (int bj = 0; bj < 2; ++bj)
; #pragma unroll
;                     for (int n = 0; n < 2; ++n) { const int g = 2 * bj + n; const f32x4 a = acc[ai][bj][m][n] + bv[g];
;                         t[0] += sigmoid_fast(a[0]) * bf2f(pw[g].x & 0xffffu); t[1] += sigmoid_fast(a[1]) * bf2f(pw[g].x >> 16);
;                         t[2] += sigmoid_fast(a[2]) * bf2f(pw[g].y & 0xffffu); t[3] += sigmoid_fast(a[3]) * bf2f(pw[g].y >> 16); }
;                 v2u w; w.x = cvt_pk_bf16(t[0], t[1]); w.y = cvt_pk_bf16(t[2], t[3]);
;                 *(v2u*)(T + (size_t)row * 1024 + oc) = w; }
	v_mov_b64_e32 v[24:25], v[216:217]
	v_mov_b64_e32 v[26:27], v[218:219]
	v_mov_b64_e32 v[20:21], v[220:221]
	v_mov_b64_e32 v[22:23], v[222:223]
	v_lshlrev_b32_e32 v32, 16, v24
	v_add_f32_e32 v15, 1.0, v15
	v_rcp_f32_e32 v30, v15
	v_rcp_f32_e32 v15, v10
	v_lshlrev_b32_e32 v33, 16, v26
	v_pk_mul_f32 v[14:15], v[14:15], v[32:33]
	s_nop 0
	v_add_f32_e32 v10, 0, v14
	v_add_f32_e32 v32, v10, v15
	v_mul_f32_e32 v10, 0xbfb8aa3b, v11
	v_exp_f32_e32 v10, v10
	v_and_b32_e32 v11, 0xffff0000, v26
	v_lshlrev_b32_e32 v15, 16, v22
	v_lshlrev_b32_e32 v14, 16, v20
	v_add_f32_e32 v10, 1.0, v10
	v_rcp_f32_e32 v29, v10
	v_and_b32_e32 v10, 0xffff0000, v24
	v_pk_mul_f32 v[10:11], v[28:29], v[10:11]
	s_nop 0
	v_add_f32_e32 v10, 0, v10
	v_add_f32_e32 v24, v10, v11
	v_mul_f32_e32 v10, 0xbfb8aa3b, v12
	v_exp_f32_e32 v10, v10
	v_lshlrev_b32_e32 v11, 16, v27
	v_add_f32_e32 v10, 1.0, v10
	v_rcp_f32_e32 v17, v10
	v_lshlrev_b32_e32 v10, 16, v25
	v_pk_mul_f32 v[10:11], v[16:17], v[10:11]
	s_nop 0
	v_add_f32_e32 v10, 0, v10
	v_add_f32_e32 v16, v10, v11
	v_mul_f32_e32 v10, 0xbfb8aa3b, v13
	v_exp_f32_e32 v10, v10
	v_and_b32_e32 v11, 0xffff0000, v27
	v_add_f32_e32 v10, 1.0, v10
	v_rcp_f32_e32 v31, v10
	v_and_b32_e32 v10, 0xffff0000, v25
	v_pk_mul_f32 v[10:11], v[30:31], v[10:11]
	s_nop 0
	v_add_f32_e32 v10, 0, v10
	v_add_f32_e32 v17, v10, v11
	v_rcp_f32_e32 v10, v7
	v_mul_f32_e32 v7, 0xbfb8aa3b, v8
	v_exp_f32_e32 v7, v7
	s_nop 0
	v_add_f32_e32 v7, 1.0, v7
	v_rcp_f32_e32 v8, v7
	v_mul_f32_e32 v7, 0xbfb8aa3b, v9
	v_exp_f32_e32 v7, v7
	s_nop 0
	v_add_f32_e32 v7, 1.0, v7
	v_rcp_f32_e32 v12, v7
	v_rcp_f32_e32 v7, v2
	s_nop 0
	v_pk_mul_f32 v[6:7], v[6:7], v[14:15]
	s_nop 0
	v_add_f32_e32 v2, v32, v6
	v_add_f32_e32 v6, v2, v7
	v_mul_f32_e32 v2, 0xbfb8aa3b, v3
	v_exp_f32_e32 v2, v2
	v_and_b32_e32 v3, 0xffff0000, v22
	v_add_f32_e32 v2, 1.0, v2
	v_rcp_f32_e32 v11, v2
	v_and_b32_e32 v2, 0xffff0000, v20
	v_pk_mul_f32 v[2:3], v[10:11], v[2:3]
	s_nop 0
	v_add_f32_e32 v2, v24, v2
	v_add_f32_e32 v7, v2, v3
	v_mul_f32_e32 v2, 0xbfb8aa3b, v4
	v_exp_f32_e32 v2, v2
	v_lshlrev_b32_e32 v3, 16, v23
	v_add_f32_e32 v2, 1.0, v2
	v_rcp_f32_e32 v9, v2
	v_lshlrev_b32_e32 v2, 16, v21
	v_pk_mul_f32 v[2:3], v[8:9], v[2:3]
	s_nop 0
	v_add_f32_e32 v2, v16, v2
	v_add_f32_e32 v4, v2, v3
	v_mul_f32_e32 v2, 0xbfb8aa3b, v5
	v_exp_f32_e32 v2, v2
	v_and_b32_e32 v3, 0xffff0000, v23
	v_add_f32_e32 v2, 1.0, v2
	v_rcp_f32_e32 v13, v2
	v_and_b32_e32 v2, 0xffff0000, v21
	v_pk_mul_f32 v[2:3], v[12:13], v[2:3]
	s_nop 0
	v_add_f32_e32 v2, v17, v2
	v_add_f32_e32 v3, v2, v3
	v_cvt_pk_bf16_f32 v2, v6, v7
	v_cvt_pk_bf16_f32 v3, v4, v3
	v_add_co_u32_e32 v4, vcc, 0x58000, v18
	s_nop 1
	v_addc_co_u32_e32 v5, vcc, 0, v19, vcc
	s_andn2_b64 vcc, exec, s[0:1]
	global_store_dwordx2 v[4:5], v[2:3], off
	s_cbranch_vccnz .LBB0_1852
	s_andn2_b64 vcc, exec, s[4:5]
	s_cbranch_vccnz .LBB0_1851
	s_barrier
	s_branch .LBB0_1851
